# adds: G4 epilogue token groups 2-4 loads prefetched one group ahead into 49 phase-free VGPRs with counted waits; G3 second group pair loads prefetched likewise
# speedup vs baseline: 1.0297x; 1.0035x over previous
; DI uint4 ld_nt16(const void* q) { const ntu4 t = __builtin_nontemporal_load((const ntu4*)q); uint4 v; v.x = t[0]; v.y = t[1]; v.z = t[2]; v.w = t[3]; return v; }
; DI float bf2f(u16 v) { return __uint_as_float(((unsigned)v) << 16); }
; DI float sigmoidf_(float x) { return frcp(1.f + __expf(-x)); }
; template <int CT>
; DI void phase_g4(int c, int l) {
;     ...
; #pragma unroll
;     for (int n = 0; n < 4; ++n) {
;       const int tl = tbase + wc * 64 + n * 16 + fr;
;       const size_t tg = (size_t)c * CT + tl;
;       const float rs = rsqrtf(WSF(ssq1)[(size_t)l * CT + tl] * (1.f / 1024.f) + EPS);
;       float ss = 0.f;
;       f32x4 xin8[8]; uint4 pp4[4];
; #pragma unroll
;       for (int m = 0; m < 8; ++m) xin8[m] = *(const f32x4*)(p.out + tg * 1024 + fbase + wr * 128 + m * 16 + fq * 4);
; #pragma unroll
;       for (int mp = 0; mp < 4; ++mp) pp4[mp] = ld_nt16(WSU(PPB) + frag_off(pm, pn, wid, n, mp, lane));
; #pragma unroll
;       for (int m = 0; m < 8; ++m) {
;         const int f = fbase + wr * 128 + m * 16 + fq * 4;
;         f32x4 xv = xin8[m];
;         uint2 pp; pp.x = (m & 1) ? pp4[m >> 1].z : pp4[m >> 1].x; pp.y = (m & 1) ? pp4[m >> 1].w : pp4[m >> 1].y;
;         xv[0] += sigmoidf_(rs * acc[m][n][0]) * bf2f(pp.x & 0xffff);
;         xv[1] += sigmoidf_(rs * acc[m][n][1]) * bf2f(pp.x >> 16);
;         xv[2] += sigmoidf_(rs * acc[m][n][2]) * bf2f(pp.y & 0xffff);
;         xv[3] += sigmoidf_(rs * acc[m][n][3]) * bf2f(pp.y >> 16);
;         *(f32x4*)(p.out + tg * 1024 + f) = xv;
;         if (l == 0) {
;           *(unsigned*)((u8*)WSU(xb) + (size_t)tl * 1024 + f) = pk4_fp8(xv[0], xv[1], xv[2], xv[3]);
;           ss += xv[0] * xv[0] + xv[1] * xv[1] + xv[2] * xv[2] + xv[3] * xv[3];
;         }
;       }
.LBB0_48:
	v_mov_b32_e32 v0, v210
	s_nop 0
	v_readfirstlane_b32 s8, v0
	s_and_b32 s7, s8, 0xc0
	v_and_or_b32 v118, v0, 15, s7
	v_or_b32_e32 v176, s6, v118
	v_ashrrev_i32_e32 v177, 31, v176
	v_lshl_add_u64 v[180:181], v[176:177], 2, s[10:11]
	global_load_dword v185, v[180:181], off
	s_ashr_i32 s44, s8, 6
	s_lshl_b64 s[6:7], s[4:5], 2
	s_add_u32 s5, s12, s6
	s_addc_u32 s15, s13, s7
	s_ashr_i32 s6, s8, 1
	s_and_b32 s6, s6, 0xffffff80
	s_ashr_i32 s7, s6, 31
	v_and_b32_e32 v184, 63, v0
	s_lshl_b64 s[8:9], s[6:7], 2
	v_lshrrev_b32_e32 v0, 2, v0
	s_add_u32 s8, s5, s8
	v_and_b32_e32 v118, 12, v0
	s_addc_u32 s9, s15, s9
	v_lshlrev_b32_e32 v0, 2, v118
	s_ashr_i32 s15, s14, 31
	s_ashr_i32 s21, s20, 31
	v_lshl_add_u64 v[178:179], s[8:9], 0, v[0:1]
	s_lshl_b64 s[8:9], s[14:15], 5
	s_lshl_b64 s[24:25], s[20:21], 3
	s_add_u32 s5, s24, s8
	s_addc_u32 s7, s25, s9
	s_ashr_i32 s9, s44, 31
	s_add_u32 s8, s5, s44
	s_addc_u32 s9, s7, s9
	s_lshl_b64 s[8:9], s[8:9], 14
	s_add_u32 s8, s36, s8
	s_addc_u32 s9, s37, s9
	s_add_i32 s4, s6, s4
	v_or_b32_e32 v174, s4, v118
	v_lshl_add_u64 v[118:119], s[54:55], 0, v[176:177]
	v_lshlrev_b64 v[182:183], 12, v[118:119]
	v_lshl_add_u64 v[118:119], v[178:179], 0, v[182:183]
	v_lshlrev_b32_e32 v0, 4, v184
	v_readlane_b32 s6, v255, 30
	v_lshl_add_u64 v[190:191], s[12:13], 0, v[182:183]
	v_lshlrev_b64 v[182:183], 10, v[176:177]
	v_readlane_b32 s7, v255, 31
	v_lshl_add_u64 v[182:183], s[16:17], 0, v[182:183]
	global_load_dwordx4 v[186:189], v[118:119], off
	global_load_dwordx4 v[166:169], v[118:119], off offset:64
	global_load_dwordx4 v[154:157], v[118:119], off offset:128
	global_load_dwordx4 v[150:153], v[118:119], off offset:192
	global_load_dwordx4 v[142:145], v[118:119], off offset:256
	global_load_dwordx4 v[138:141], v[118:119], off offset:320
	global_load_dwordx4 v[126:129], v[118:119], off offset:384
	s_nop 0
	global_load_dwordx4 v[118:121], v[118:119], off offset:448
	s_nop 0
	global_load_dwordx4 v[170:173], v0, s[8:9] nt
	global_load_dwordx4 v[162:165], v0, s[8:9] offset:1024 nt
	global_load_dwordx4 v[146:149], v0, s[8:9] offset:2048 nt
	global_load_dwordx4 v[134:137], v0, s[8:9] offset:3072 nt
	s_waitcnt vmcnt(12)
	v_fmamk_f32 v185, v185, 0x3a800000, v211
	v_cmp_gt_f32_e32 vcc, s88, v185
	v_mul_f32_e32 v175, 0x4b800000, v185
	s_nop 0
	v_cndmask_b32_e32 v185, v185, v175, vcc
	v_rsq_f32_e32 v175, v185
	s_nop 0
	v_mul_f32_e32 v185, 0x45800000, v175
	v_cndmask_b32_e32 v185, v175, v185, vcc
	v_mul_f32_e32 v158, v158, v185
	v_mul_f32_e32 v159, v159, v185
	v_mul_f32_e32 v158, 0xbfb8aa3b, v158
	v_mul_f32_e32 v159, 0xbfb8aa3b, v159
	v_mul_f32_e32 v160, v160, v185
	v_mul_f32_e32 v161, v161, v185
	v_exp_f32_e32 v158, v158
	v_exp_f32_e32 v159, v159
	v_mul_f32_e32 v160, 0xbfb8aa3b, v160
	v_mul_f32_e32 v161, 0xbfb8aa3b, v161
	v_exp_f32_e32 v160, v160
	v_exp_f32_e32 v161, v161
	v_add_f32_e32 v158, 1.0, v158
	v_add_f32_e32 v159, 1.0, v159
	v_rcp_f32_e32 v158, v158
	v_rcp_f32_e32 v159, v159
	v_add_f32_e32 v160, 1.0, v160
	v_add_f32_e32 v161, 1.0, v161
	v_rcp_f32_e32 v160, v160
	v_rcp_f32_e32 v161, v161
	v_ashrrev_i32_e32 v175, 31, v174
	s_andn2_b64 vcc, exec, s[6:7]
	v_lshl_add_u64 v[182:183], v[182:183], 0, v[174:175]
	s_waitcnt vmcnt(0)
	global_load_dword v254, v[180:181], off offset:64
	v_lshl_add_u64 v[206:207], s[8:9], 0, v[0:1]
	v_lshl_add_u64 v[206:207], 64, 4, v[206:207]
	v_lshl_add_u64 v[206:207], 64, 4, v[206:207]
	v_lshl_add_u64 v[206:207], 64, 4, v[206:207]
	v_lshl_add_u64 v[206:207], 64, 4, v[206:207]
	global_load_dwordx4 v[194:197], v[206:207], off nt
	global_load_dwordx4 v[198:201], v[206:207], off offset:1024 nt
	global_load_dwordx4 v[202:205], v[206:207], off offset:2048 nt
	s_nop 0
	global_load_dwordx4 v[206:209], v[206:207], off offset:3072 nt
	v_or_b32_e32 v248, 16, v176
	v_ashrrev_i32_e32 v249, 31, v248
	v_lshl_add_u64 v[248:249], s[54:55], 0, v[248:249]
	v_lshlrev_b64 v[248:249], 12, v[248:249]
	v_lshl_add_u64 v[248:249], v[178:179], 0, v[248:249]
	global_load_dwordx4 v[216:219], v[248:249], off
	global_load_dwordx4 v[222:225], v[248:249], off offset:64
	global_load_dwordx4 v[226:229], v[248:249], off offset:128
	global_load_dwordx4 v[232:235], v[248:249], off offset:192
	global_load_dwordx4 v[236:239], v[248:249], off offset:256
	global_load_dwordx4 v[240:243], v[248:249], off offset:320
	global_load_dwordx4 v[244:247], v[248:249], off offset:384
	s_nop 0
	global_load_dwordx4 v[248:251], v[248:249], off offset:448
	v_lshlrev_b32_e32 v192, 16, v170
	v_and_b32_e32 v193, 0xffff0000, v170
	v_pk_fma_f32 v[158:159], v[158:159], v[192:193], v[186:187]
	v_and_b32_e32 v187, 0xffff0000, v171
	v_lshlrev_b32_e32 v186, 16, v171
	v_pk_fma_f32 v[160:161], v[160:161], v[186:187], v[188:189]
	v_cndmask_b32_e64 v187, 0, 1, s[6:7]
	v_lshl_add_u64 v[170:171], v[174:175], 2, v[190:191]
	v_mov_b32_e32 v186, 0
	v_cmp_ne_u32_e64 s[4:5], 1, v187
	global_store_dwordx4 v[170:171], v[158:161], off
	s_cbranch_vccnz .LBB0_50
	v_mov_b32_e32 v188, v1
	v_cvt_pk_fp8_f32 v188, v158, v159
	v_pk_mul_f32 v[158:159], v[158:159], v[158:159]
	v_pk_mul_f32 v[186:187], v[160:161], v[160:161]
	v_add_f32_e32 v158, v158, v159
	v_cvt_pk_fp8_f32 v188, v160, v161 op_sel:[0,0,1]
	v_add_f32_e32 v158, v186, v158
	v_add_f32_e32 v186, v187, v158
	global_store_dword v[182:183], v188, off

; DI uint4 ld_nt16(const void* q) { const ntu4 t = __builtin_nontemporal_load((const ntu4*)q); uint4 v; v.x = t[0]; v.y = t[1]; v.z = t[2]; v.w = t[3]; return v; }
; DI float bf2f(u16 v) { return __uint_as_float(((unsigned)v) << 16); }
; DI float sigmoidf_(float x) { return frcp(1.f + __expf(-x)); }
; template <int CT>
; DI void phase_g4(int c, int l) {
;     ...
;     for (int n = 0; n < 4; ++n) {
;       const int tl = tbase + wc * 64 + n * 16 + fr;
;       const size_t tg = (size_t)c * CT + tl;
;       const float rs = rsqrtf(WSF(ssq1)[(size_t)l * CT + tl] * (1.f / 1024.f) + EPS);
;       float ss = 0.f;
;       f32x4 xin8[8]; uint4 pp4[4];
; #pragma unroll
;       for (int m = 0; m < 8; ++m) xin8[m] = *(const f32x4*)(p.out + tg * 1024 + fbase + wr * 128 + m * 16 + fq * 4);
; #pragma unroll
;       for (int mp = 0; mp < 4; ++mp) pp4[mp] = ld_nt16(WSU(PPB) + frag_off(pm, pn, wid, n, mp, lane));
; #pragma unroll
;       for (int m = 0; m < 8; ++m) {
;         const int f = fbase + wr * 128 + m * 16 + fq * 4;
;         f32x4 xv = xin8[m];
;         uint2 pp; pp.x = (m & 1) ? pp4[m >> 1].z : pp4[m >> 1].x; pp.y = (m & 1) ? pp4[m >> 1].w : pp4[m >> 1].y;
;         xv[0] += sigmoidf_(rs * acc[m][n][0]) * bf2f(pp.x & 0xffff);
;         xv[1] += sigmoidf_(rs * acc[m][n][1]) * bf2f(pp.x >> 16);
;         xv[2] += sigmoidf_(rs * acc[m][n][2]) * bf2f(pp.y & 0xffff);
;         xv[3] += sigmoidf_(rs * acc[m][n][3]) * bf2f(pp.y >> 16);
;         *(f32x4*)(p.out + tg * 1024 + f) = xv;
;         if (l == 0) {
;           *(unsigned*)((u8*)WSU(xb) + (size_t)tl * 1024 + f) = pk4_fp8(xv[0], xv[1], xv[2], xv[3]);
;           ss += xv[0] * xv[0] + xv[1] * xv[1] + xv[2] * xv[2] + xv[3] * xv[3];
;         }
;       }
.LBB0_66:
	v_lshl_add_u64 v[142:143], s[8:9], 0, v[0:1]
	v_add_co_u32_e32 v98, vcc, s89, v142
	v_or_b32_e32 v144, 16, v176
	s_nop 0
	v_addc_co_u32_e32 v99, vcc, 0, v143, vcc
	s_nop 0
	v_ashrrev_i32_e32 v145, 31, v144
	v_lshl_add_u64 v[102:103], s[54:55], 0, v[144:145]
	v_lshlrev_b64 v[146:147], 12, v[102:103]
	v_lshl_add_u64 v[102:103], v[178:179], 0, v[146:147]
	s_nop 0
	v_lshlrev_b64 v[148:149], 10, v[144:145]
	v_lshl_add_u64 v[154:155], s[16:17], 0, v[148:149]
	v_lshl_add_u64 v[146:147], s[12:13], 0, v[146:147]
	v_mov_b32_e32 v0, 0
	s_and_b64 vcc, exec, s[4:5]
	v_lshl_add_u64 v[146:147], v[174:175], 2, v[146:147]
	s_waitcnt vmcnt(8)
	v_mov_b32_e32 v156, v254
	v_mov_b32_e32 v134, v194
	v_mov_b32_e32 v135, v195
	v_mov_b32_e32 v136, v196
	v_mov_b32_e32 v137, v197
	v_mov_b32_e32 v122, v198
	v_mov_b32_e32 v123, v199
	v_mov_b32_e32 v124, v200
	v_mov_b32_e32 v125, v201
	v_mov_b32_e32 v110, v202
	v_mov_b32_e32 v111, v203
	v_mov_b32_e32 v112, v204
	v_mov_b32_e32 v113, v205
	v_mov_b32_e32 v98, v206
	v_mov_b32_e32 v99, v207
	v_mov_b32_e32 v100, v208
	v_mov_b32_e32 v101, v209
	v_mov_b32_e32 v150, v216
	v_mov_b32_e32 v151, v217
	v_mov_b32_e32 v152, v218
	v_mov_b32_e32 v153, v219
	v_mov_b32_e32 v138, v222
	v_mov_b32_e32 v139, v223
	v_mov_b32_e32 v140, v224
	v_mov_b32_e32 v141, v225
	v_mov_b32_e32 v130, v226
	v_mov_b32_e32 v131, v227
	v_mov_b32_e32 v132, v228
	v_mov_b32_e32 v133, v229
	v_mov_b32_e32 v126, v232
	v_mov_b32_e32 v127, v233
	v_mov_b32_e32 v128, v234
	v_mov_b32_e32 v129, v235
	v_mov_b32_e32 v118, v236
	v_mov_b32_e32 v119, v237
	v_mov_b32_e32 v120, v238
	v_mov_b32_e32 v121, v239
	v_mov_b32_e32 v114, v240
	v_mov_b32_e32 v115, v241
	v_mov_b32_e32 v116, v242
	v_mov_b32_e32 v117, v243
	v_mov_b32_e32 v106, v244
	v_mov_b32_e32 v107, v245
	v_mov_b32_e32 v108, v246
	v_mov_b32_e32 v109, v247
	v_mov_b32_e32 v102, v248
	v_mov_b32_e32 v103, v249
	v_mov_b32_e32 v104, v250
	v_mov_b32_e32 v105, v251
	global_load_dword v254, v[180:181], off offset:128
	v_mov_b32_e32 v206, v142
	v_mov_b32_e32 v207, v143
	v_lshl_add_u64 v[206:207], 64, 4, v[206:207]
	v_lshl_add_u64 v[206:207], 64, 4, v[206:207]
	v_lshl_add_u64 v[206:207], 64, 4, v[206:207]
	v_lshl_add_u64 v[206:207], 64, 4, v[206:207]
	v_lshl_add_u64 v[206:207], 64, 4, v[206:207]
	v_lshl_add_u64 v[206:207], 64, 4, v[206:207]
	v_lshl_add_u64 v[206:207], 64, 4, v[206:207]
	v_lshl_add_u64 v[206:207], 64, 4, v[206:207]
	global_load_dwordx4 v[194:197], v[206:207], off nt
	global_load_dwordx4 v[198:201], v[206:207], off offset:1024 nt
	global_load_dwordx4 v[202:205], v[206:207], off offset:2048 nt
	s_nop 0
	global_load_dwordx4 v[206:209], v[206:207], off offset:3072 nt
	v_or_b32_e32 v248, 32, v176
	v_ashrrev_i32_e32 v249, 31, v248
	v_lshl_add_u64 v[248:249], s[54:55], 0, v[248:249]
	v_lshlrev_b64 v[248:249], 12, v[248:249]
	v_lshl_add_u64 v[248:249], v[178:179], 0, v[248:249]
	global_load_dwordx4 v[216:219], v[248:249], off
	global_load_dwordx4 v[222:225], v[248:249], off offset:64
	global_load_dwordx4 v[226:229], v[248:249], off offset:128
	global_load_dwordx4 v[232:235], v[248:249], off offset:192
	global_load_dwordx4 v[236:239], v[248:249], off offset:256
	global_load_dwordx4 v[240:243], v[248:249], off offset:320
	global_load_dwordx4 v[244:247], v[248:249], off offset:384
	s_nop 0
	global_load_dwordx4 v[248:251], v[248:249], off offset:448
	v_fmamk_f32 v148, v156, 0x3a800000, v211
	v_mul_f32_e32 v149, 0x4b800000, v148
	v_cmp_gt_f32_e64 s[8:9], s88, v148
	v_lshlrev_b32_e32 v156, 16, v134
	s_nop 0
	v_cndmask_b32_e64 v148, v148, v149, s[8:9]
	v_rsq_f32_e32 v148, v148
	v_and_b32_e32 v157, 0xffff0000, v134
	v_and_b32_e32 v159, 0xffff0000, v135
	v_lshlrev_b32_e32 v158, 16, v135
	v_mul_f32_e32 v134, 0x45800000, v148
	v_cndmask_b32_e64 v148, v148, v134, s[8:9]
	v_mul_f32_e32 v94, v94, v148
	v_mul_f32_e32 v95, v95, v148
	v_mul_f32_e32 v96, v96, v148
	v_mul_f32_e32 v97, v97, v148
	v_mul_f32_e32 v94, 0xbfb8aa3b, v94
	v_mul_f32_e32 v95, 0xbfb8aa3b, v95
	v_mul_f32_e32 v96, 0xbfb8aa3b, v96
	v_mul_f32_e32 v97, 0xbfb8aa3b, v97
	v_exp_f32_e32 v94, v94
	v_exp_f32_e32 v95, v95
	v_exp_f32_e32 v96, v96
	v_exp_f32_e32 v97, v97
	v_add_f32_e32 v94, 1.0, v94
	v_add_f32_e32 v95, 1.0, v95
	v_add_f32_e32 v96, 1.0, v96
	v_add_f32_e32 v97, 1.0, v97
	v_rcp_f32_e32 v94, v94
	v_rcp_f32_e32 v95, v95
	v_rcp_f32_e32 v96, v96
	v_rcp_f32_e32 v97, v97
	v_lshl_add_u64 v[134:135], v[154:155], 0, v[174:175]
	v_pk_fma_f32 v[94:95], v[94:95], v[156:157], v[150:151]
	v_pk_fma_f32 v[96:97], v[96:97], v[158:159], v[152:153]
	global_store_dwordx4 v[146:147], v[94:97], off
	s_cbranch_vccnz .LBB0_68
	v_mov_b32_e32 v149, v1
	v_cvt_pk_fp8_f32 v149, v94, v95
	v_pk_mul_f32 v[94:95], v[94:95], v[94:95]
	v_pk_mul_f32 v[150:151], v[96:97], v[96:97]
	v_add_f32_e32 v0, v94, v95
	v_cvt_pk_fp8_f32 v149, v96, v97 op_sel:[0,0,1]
	v_add_f32_e32 v0, v150, v0
	v_add_f32_e32 v0, v151, v0
	global_store_dword v[134:135], v149, off

; DI uint4 ld_nt16(const void* q) { const ntu4 t = __builtin_nontemporal_load((const ntu4*)q); uint4 v; v.x = t[0]; v.y = t[1]; v.z = t[2]; v.w = t[3]; return v; }
; DI float bf2f(u16 v) { return __uint_as_float(((unsigned)v) << 16); }
; DI float sigmoidf_(float x) { return frcp(1.f + __expf(-x)); }
; template <int CT>
; DI void phase_g4(int c, int l) {
;     ...
;     for (int n = 0; n < 4; ++n) {
;       const int tl = tbase + wc * 64 + n * 16 + fr;
;       const size_t tg = (size_t)c * CT + tl;
;       const float rs = rsqrtf(WSF(ssq1)[(size_t)l * CT + tl] * (1.f / 1024.f) + EPS);
;       float ss = 0.f;
;       f32x4 xin8[8]; uint4 pp4[4];
; #pragma unroll
;       for (int m = 0; m < 8; ++m) xin8[m] = *(const f32x4*)(p.out + tg * 1024 + fbase + wr * 128 + m * 16 + fq * 4);
; #pragma unroll
;       for (int mp = 0; mp < 4; ++mp) pp4[mp] = ld_nt16(WSU(PPB) + frag_off(pm, pn, wid, n, mp, lane));
; #pragma unroll
;       for (int m = 0; m < 8; ++m) {
;         const int f = fbase + wr * 128 + m * 16 + fq * 4;
;         f32x4 xv = xin8[m];
;         uint2 pp; pp.x = (m & 1) ? pp4[m >> 1].z : pp4[m >> 1].x; pp.y = (m & 1) ? pp4[m >> 1].w : pp4[m >> 1].y;
;         xv[0] += sigmoidf_(rs * acc[m][n][0]) * bf2f(pp.x & 0xffff);
;         xv[1] += sigmoidf_(rs * acc[m][n][1]) * bf2f(pp.x >> 16);
;         xv[2] += sigmoidf_(rs * acc[m][n][2]) * bf2f(pp.y & 0xffff);
;         xv[3] += sigmoidf_(rs * acc[m][n][3]) * bf2f(pp.y >> 16);
;         *(f32x4*)(p.out + tg * 1024 + f) = xv;
;         if (l == 0) {
;           *(unsigned*)((u8*)WSU(xb) + (size_t)tl * 1024 + f) = pk4_fp8(xv[0], xv[1], xv[2], xv[3]);
;           ss += xv[0] * xv[0] + xv[1] * xv[1] + xv[2] * xv[2] + xv[3] * xv[3];
;         }
;       }
.LBB0_84:
	v_add_co_u32_e32 v66, vcc, s95, v142
	v_or_b32_e32 v110, 32, v176
	s_nop 0
	v_addc_co_u32_e32 v67, vcc, 0, v143, vcc
	s_nop 0
	v_ashrrev_i32_e32 v111, 31, v110
	v_lshl_add_u64 v[70:71], s[54:55], 0, v[110:111]
	v_lshlrev_b64 v[112:113], 12, v[70:71]
	v_lshl_add_u64 v[70:71], v[178:179], 0, v[112:113]
	s_nop 0
	v_lshlrev_b64 v[114:115], 10, v[110:111]
	v_lshl_add_u64 v[120:121], s[16:17], 0, v[114:115]
	v_lshl_add_u64 v[112:113], s[12:13], 0, v[112:113]
	v_mov_b32_e32 v0, 0
	s_and_b64 vcc, exec, s[4:5]
	v_lshl_add_u64 v[112:113], v[174:175], 2, v[112:113]
	s_waitcnt vmcnt(8)
	v_mov_b32_e32 v122, v254
	v_mov_b32_e32 v102, v194
	v_mov_b32_e32 v103, v195
	v_mov_b32_e32 v104, v196
	v_mov_b32_e32 v105, v197
	v_mov_b32_e32 v90, v198
	v_mov_b32_e32 v91, v199
	v_mov_b32_e32 v92, v200
	v_mov_b32_e32 v93, v201
	v_mov_b32_e32 v78, v202
	v_mov_b32_e32 v79, v203
	v_mov_b32_e32 v80, v204
	v_mov_b32_e32 v81, v205
	v_mov_b32_e32 v66, v206
	v_mov_b32_e32 v67, v207
	v_mov_b32_e32 v68, v208
	v_mov_b32_e32 v69, v209
	v_mov_b32_e32 v116, v216
	v_mov_b32_e32 v117, v217
	v_mov_b32_e32 v118, v218
	v_mov_b32_e32 v119, v219
	v_mov_b32_e32 v106, v222
	v_mov_b32_e32 v107, v223
	v_mov_b32_e32 v108, v224
	v_mov_b32_e32 v109, v225
	v_mov_b32_e32 v98, v226
	v_mov_b32_e32 v99, v227
	v_mov_b32_e32 v100, v228
	v_mov_b32_e32 v101, v229
	v_mov_b32_e32 v94, v232
	v_mov_b32_e32 v95, v233
	v_mov_b32_e32 v96, v234
	v_mov_b32_e32 v97, v235
	v_mov_b32_e32 v86, v236
	v_mov_b32_e32 v87, v237
	v_mov_b32_e32 v88, v238
	v_mov_b32_e32 v89, v239
	v_mov_b32_e32 v82, v240
	v_mov_b32_e32 v83, v241
	v_mov_b32_e32 v84, v242
	v_mov_b32_e32 v85, v243
	v_mov_b32_e32 v74, v244
	v_mov_b32_e32 v75, v245
	v_mov_b32_e32 v76, v246
	v_mov_b32_e32 v77, v247
	v_mov_b32_e32 v70, v248
	v_mov_b32_e32 v71, v249
	v_mov_b32_e32 v72, v250
	v_mov_b32_e32 v73, v251
	global_load_dword v254, v[180:181], off offset:192
	v_mov_b32_e32 v206, v142
	v_mov_b32_e32 v207, v143
	v_lshl_add_u64 v[206:207], 64, 4, v[206:207]
	v_lshl_add_u64 v[206:207], 64, 4, v[206:207]
	v_lshl_add_u64 v[206:207], 64, 4, v[206:207]
	v_lshl_add_u64 v[206:207], 64, 4, v[206:207]
	v_lshl_add_u64 v[206:207], 64, 4, v[206:207]
	v_lshl_add_u64 v[206:207], 64, 4, v[206:207]
	v_lshl_add_u64 v[206:207], 64, 4, v[206:207]
	v_lshl_add_u64 v[206:207], 64, 4, v[206:207]
	v_lshl_add_u64 v[206:207], 64, 4, v[206:207]
	v_lshl_add_u64 v[206:207], 64, 4, v[206:207]
	v_lshl_add_u64 v[206:207], 64, 4, v[206:207]
	v_lshl_add_u64 v[206:207], 64, 4, v[206:207]
	global_load_dwordx4 v[194:197], v[206:207], off nt
	global_load_dwordx4 v[198:201], v[206:207], off offset:1024 nt
	global_load_dwordx4 v[202:205], v[206:207], off offset:2048 nt
	s_nop 0
	global_load_dwordx4 v[206:209], v[206:207], off offset:3072 nt
	v_or_b32_e32 v248, 48, v176
	v_ashrrev_i32_e32 v249, 31, v248
	v_lshl_add_u64 v[248:249], s[54:55], 0, v[248:249]
	v_lshlrev_b64 v[248:249], 12, v[248:249]
	v_lshl_add_u64 v[248:249], v[178:179], 0, v[248:249]
	global_load_dwordx4 v[216:219], v[248:249], off
	global_load_dwordx4 v[222:225], v[248:249], off offset:64
	global_load_dwordx4 v[226:229], v[248:249], off offset:128
	global_load_dwordx4 v[232:235], v[248:249], off offset:192
	global_load_dwordx4 v[236:239], v[248:249], off offset:256
	global_load_dwordx4 v[240:243], v[248:249], off offset:320
	global_load_dwordx4 v[244:247], v[248:249], off offset:384
	s_nop 0
	global_load_dwordx4 v[248:251], v[248:249], off offset:448
	v_fmamk_f32 v114, v122, 0x3a800000, v211
	v_mul_f32_e32 v115, 0x4b800000, v114
	v_cmp_gt_f32_e64 s[8:9], s88, v114
	v_lshlrev_b32_e32 v122, 16, v102
	s_nop 0
	v_cndmask_b32_e64 v114, v114, v115, s[8:9]
	v_rsq_f32_e32 v114, v114
	v_and_b32_e32 v123, 0xffff0000, v102
	v_and_b32_e32 v125, 0xffff0000, v103
	v_lshlrev_b32_e32 v124, 16, v103
	v_mul_f32_e32 v102, 0x45800000, v114
	v_cndmask_b32_e64 v114, v114, v102, s[8:9]
	v_mul_f32_e32 v62, v62, v114
	v_mul_f32_e32 v63, v63, v114
	v_mul_f32_e32 v64, v64, v114
	v_mul_f32_e32 v65, v65, v114
	v_mul_f32_e32 v62, 0xbfb8aa3b, v62
	v_mul_f32_e32 v63, 0xbfb8aa3b, v63
	v_mul_f32_e32 v64, 0xbfb8aa3b, v64
	v_mul_f32_e32 v65, 0xbfb8aa3b, v65
	v_exp_f32_e32 v62, v62
	v_exp_f32_e32 v63, v63
	v_exp_f32_e32 v64, v64
	v_exp_f32_e32 v65, v65
	v_add_f32_e32 v62, 1.0, v62
	v_add_f32_e32 v63, 1.0, v63
	v_add_f32_e32 v64, 1.0, v64
	v_add_f32_e32 v65, 1.0, v65
	v_rcp_f32_e32 v62, v62
	v_rcp_f32_e32 v63, v63
	v_rcp_f32_e32 v64, v64
	v_rcp_f32_e32 v65, v65
	v_lshl_add_u64 v[102:103], v[120:121], 0, v[174:175]
	v_pk_fma_f32 v[62:63], v[62:63], v[122:123], v[116:117]
	v_pk_fma_f32 v[64:65], v[64:65], v[124:125], v[118:119]
	global_store_dwordx4 v[112:113], v[62:65], off
	s_cbranch_vccnz .LBB0_86
	v_mov_b32_e32 v115, v1
	v_cvt_pk_fp8_f32 v115, v62, v63
	v_pk_mul_f32 v[62:63], v[62:63], v[62:63]
	v_pk_mul_f32 v[116:117], v[64:65], v[64:65]
	v_add_f32_e32 v0, v62, v63
	v_cvt_pk_fp8_f32 v115, v64, v65 op_sel:[0,0,1]
	v_add_f32_e32 v0, v116, v0
	v_add_f32_e32 v0, v117, v0
	global_store_dword v[102:103], v115, off

; DI uint4 ld_nt16(const void* q) { const ntu4 t = __builtin_nontemporal_load((const ntu4*)q); uint4 v; v.x = t[0]; v.y = t[1]; v.z = t[2]; v.w = t[3]; return v; }
; DI float bf2f(u16 v) { return __uint_as_float(((unsigned)v) << 16); }
; DI float sigmoidf_(float x) { return frcp(1.f + __expf(-x)); }
; template <int CT>
; DI void phase_g4(int c, int l) {
;     ...
;     for (int n = 0; n < 4; ++n) {
;       const int tl = tbase + wc * 64 + n * 16 + fr;
;       const size_t tg = (size_t)c * CT + tl;
;       const float rs = rsqrtf(WSF(ssq1)[(size_t)l * CT + tl] * (1.f / 1024.f) + EPS);
;       float ss = 0.f;
;       f32x4 xin8[8]; uint4 pp4[4];
; #pragma unroll
;       for (int m = 0; m < 8; ++m) xin8[m] = *(const f32x4*)(p.out + tg * 1024 + fbase + wr * 128 + m * 16 + fq * 4);
; #pragma unroll
;       for (int mp = 0; mp < 4; ++mp) pp4[mp] = ld_nt16(WSU(PPB) + frag_off(pm, pn, wid, n, mp, lane));
; #pragma unroll
;       for (int m = 0; m < 8; ++m) {
;         const int f = fbase + wr * 128 + m * 16 + fq * 4;
;         f32x4 xv = xin8[m];
;         uint2 pp; pp.x = (m & 1) ? pp4[m >> 1].z : pp4[m >> 1].x; pp.y = (m & 1) ? pp4[m >> 1].w : pp4[m >> 1].y;
;         xv[0] += sigmoidf_(rs * acc[m][n][0]) * bf2f(pp.x & 0xffff);
;         xv[1] += sigmoidf_(rs * acc[m][n][1]) * bf2f(pp.x >> 16);
;         xv[2] += sigmoidf_(rs * acc[m][n][2]) * bf2f(pp.y & 0xffff);
;         xv[3] += sigmoidf_(rs * acc[m][n][3]) * bf2f(pp.y >> 16);
;         *(f32x4*)(p.out + tg * 1024 + f) = xv;
;         if (l == 0) {
;           *(unsigned*)((u8*)WSU(xb) + (size_t)tl * 1024 + f) = pk4_fp8(xv[0], xv[1], xv[2], xv[3]);
;           ss += xv[0] * xv[0] + xv[1] * xv[1] + xv[2] * xv[2] + xv[3] * xv[3];
;         }
;       }
.LBB0_102:
	s_movk_i32 s8, 0x3000
	v_add_co_u32_e32 v34, vcc, s8, v142
	v_or_b32_e32 v78, 48, v176
	s_nop 0
	v_addc_co_u32_e32 v35, vcc, 0, v143, vcc
	s_nop 0
	v_ashrrev_i32_e32 v79, 31, v78
	v_lshl_add_u64 v[38:39], s[54:55], 0, v[78:79]
	v_lshlrev_b64 v[80:81], 12, v[38:39]
	v_lshl_add_u64 v[38:39], v[178:179], 0, v[80:81]
	s_nop 0
	v_lshlrev_b64 v[82:83], 10, v[78:79]
	v_lshl_add_u64 v[88:89], s[16:17], 0, v[82:83]
	v_lshl_add_u64 v[80:81], s[12:13], 0, v[80:81]
	v_mov_b32_e32 v0, 0
	s_and_b64 vcc, exec, s[4:5]
	v_lshl_add_u64 v[80:81], v[174:175], 2, v[80:81]
	s_waitcnt vmcnt(8)
	v_mov_b32_e32 v90, v254
	v_mov_b32_e32 v70, v194
	v_mov_b32_e32 v71, v195
	v_mov_b32_e32 v72, v196
	v_mov_b32_e32 v73, v197
	v_mov_b32_e32 v58, v198
	v_mov_b32_e32 v59, v199
	v_mov_b32_e32 v60, v200
	v_mov_b32_e32 v61, v201
	v_mov_b32_e32 v46, v202
	v_mov_b32_e32 v47, v203
	v_mov_b32_e32 v48, v204
	v_mov_b32_e32 v49, v205
	v_mov_b32_e32 v34, v206
	v_mov_b32_e32 v35, v207
	v_mov_b32_e32 v36, v208
	v_mov_b32_e32 v37, v209
	v_mov_b32_e32 v84, v216
	v_mov_b32_e32 v85, v217
	v_mov_b32_e32 v86, v218
	v_mov_b32_e32 v87, v219
	v_mov_b32_e32 v74, v222
	v_mov_b32_e32 v75, v223
	v_mov_b32_e32 v76, v224
	v_mov_b32_e32 v77, v225
	v_mov_b32_e32 v66, v226
	v_mov_b32_e32 v67, v227
	v_mov_b32_e32 v68, v228
	v_mov_b32_e32 v69, v229
	v_mov_b32_e32 v62, v232
	v_mov_b32_e32 v63, v233
	v_mov_b32_e32 v64, v234
	v_mov_b32_e32 v65, v235
	v_mov_b32_e32 v54, v236
	v_mov_b32_e32 v55, v237
	v_mov_b32_e32 v56, v238
	v_mov_b32_e32 v57, v239
	v_mov_b32_e32 v50, v240
	v_mov_b32_e32 v51, v241
	v_mov_b32_e32 v52, v242
	v_mov_b32_e32 v53, v243
	v_mov_b32_e32 v42, v244
	v_mov_b32_e32 v43, v245
	v_mov_b32_e32 v44, v246
	v_mov_b32_e32 v45, v247
	v_mov_b32_e32 v38, v248
	v_mov_b32_e32 v39, v249
	v_mov_b32_e32 v40, v250
	v_mov_b32_e32 v41, v251
	v_fmamk_f32 v82, v90, 0x3a800000, v211
	v_mul_f32_e32 v83, 0x4b800000, v82
	v_cmp_gt_f32_e64 s[8:9], s88, v82
	v_lshlrev_b32_e32 v90, 16, v70
	s_nop 0
	v_cndmask_b32_e64 v82, v82, v83, s[8:9]
	v_rsq_f32_e32 v82, v82
	v_and_b32_e32 v91, 0xffff0000, v70
	v_and_b32_e32 v93, 0xffff0000, v71
	v_lshlrev_b32_e32 v92, 16, v71
	v_mul_f32_e32 v70, 0x45800000, v82
	v_cndmask_b32_e64 v82, v82, v70, s[8:9]
	v_mul_f32_e32 v30, v30, v82
	v_mul_f32_e32 v31, v31, v82
	v_mul_f32_e32 v32, v32, v82
	v_mul_f32_e32 v33, v33, v82
	v_mul_f32_e32 v30, 0xbfb8aa3b, v30
	v_mul_f32_e32 v31, 0xbfb8aa3b, v31
	v_mul_f32_e32 v32, 0xbfb8aa3b, v32
	v_mul_f32_e32 v33, 0xbfb8aa3b, v33
	v_exp_f32_e32 v30, v30
	v_exp_f32_e32 v31, v31
	v_exp_f32_e32 v32, v32
	v_exp_f32_e32 v33, v33
	v_add_f32_e32 v30, 1.0, v30
	v_add_f32_e32 v31, 1.0, v31
	v_add_f32_e32 v32, 1.0, v32
	v_add_f32_e32 v33, 1.0, v33
	v_rcp_f32_e32 v30, v30
	v_rcp_f32_e32 v31, v31
	v_rcp_f32_e32 v32, v32
	v_rcp_f32_e32 v33, v33
	v_lshl_add_u64 v[70:71], v[88:89], 0, v[174:175]
	v_pk_fma_f32 v[30:31], v[30:31], v[90:91], v[84:85]
	v_pk_fma_f32 v[32:33], v[32:33], v[92:93], v[86:87]
	global_store_dwordx4 v[80:81], v[30:33], off
	s_cbranch_vccnz .LBB0_104
	v_mov_b32_e32 v83, v1
	v_cvt_pk_fp8_f32 v83, v30, v31
	v_pk_mul_f32 v[30:31], v[30:31], v[30:31]
	v_pk_mul_f32 v[84:85], v[32:33], v[32:33]
	v_add_f32_e32 v0, v30, v31
	v_cvt_pk_fp8_f32 v83, v32, v33 op_sel:[0,0,1]
	v_add_f32_e32 v0, v84, v0
	v_add_f32_e32 v0, v85, v0
	global_store_dword v[70:71], v83, off

; template <int CT>
; DI void phase_g3(int c, int l) {
;     ...
;     for (int n2 = 0; n2 < 4; n2 += 2) {
;       f32x4 xin16[2][8];
; #pragma unroll
;       for (int nn = 0; nn < 2; ++nn) {
;         const size_t tg = (size_t)c * CT + tbase + wc * 64 + (n2 + nn) * 16 + fr;
;         const float* xin = l == 0 ? (tg < NTOK_PROMPT ? p.x_in0 + tg * 1024 : p.x_in1 + (tg - NTOK_PROMPT) * 1024) : p.out + tg * 1024;
; #pragma unroll
;         for (int m = 0; m < 8; ++m) xin16[nn][m] = *(const f32x4*)(xin + fbase + wr * 128 + m * 16 + fq * 4);
;       }
.LBB0_171:
	s_ashr_i32 s5, s26, 1
	s_and_b32 s26, s5, 0xffffff80
	v_bfe_u32 v135, v0, 4, 2
	s_ashr_i32 s27, s26, 31
	v_lshl_add_u64 v[126:127], s[18:19], 2, v[126:127]
	v_lshl_add_u64 v[126:127], s[26:27], 2, v[126:127]
	v_lshlrev_b32_e32 v0, 4, v135
	v_lshl_add_u64 v[126:127], v[126:127], 0, v[0:1]
	v_mov_b32_e32 v208, v126
	v_mov_b32_e32 v209, v127
	global_load_dwordx4 v[190:193], v[126:127], off
	global_load_dwordx4 v[186:189], v[126:127], off offset:64
	global_load_dwordx4 v[182:185], v[126:127], off offset:128
	global_load_dwordx4 v[178:181], v[126:127], off offset:192
	global_load_dwordx4 v[174:177], v[126:127], off offset:256
	global_load_dwordx4 v[170:173], v[126:127], off offset:320
	global_load_dwordx4 v[166:169], v[126:127], off offset:384
	global_load_dwordx4 v[158:161], v[126:127], off offset:448
	v_or_b32_e32 v126, 16, v198
	v_mov_b32_e32 v127, v199
	v_cndmask_b32_e64 v0, 0, 1, s[60:61]
	s_mov_b64 s[28:29], -1
	v_cmp_ne_u32_e64 s[8:9], 1, v0
	s_andn2_b64 vcc, exec, s[60:61]
	v_lshlrev_b64 v[128:129], 12, v[126:127]
	s_cbranch_vccnz .LBB0_173
	v_lshl_add_u64 v[126:127], s[16:17], 0, v[128:129]
	s_mov_b64 s[28:29], 0

; DI float xsum16(float x) { const u32x2 r = __builtin_amdgcn_permlane16_swap(__float_as_uint(x), __float_as_uint(x), false, false); return __uint_as_float(r[0]) + __uint_as_float(r[1]); }
; DI float xsum32(float x) { const u32x2 r = __builtin_amdgcn_permlane32_swap(__float_as_uint(x), __float_as_uint(x), false, false); return __uint_as_float(r[0]) + __uint_as_float(r[1]); }
; template <int CT>
; DI void phase_g3(int c, int l) {
;     ...
;     for (int n2 = 0; n2 < 4; n2 += 2) {
;       f32x4 xin16[2][8];
; #pragma unroll
;       for (int nn = 0; nn < 2; ++nn) {
;         const size_t tg = (size_t)c * CT + tbase + wc * 64 + (n2 + nn) * 16 + fr;
;         const float* xin = l == 0 ? (tg < NTOK_PROMPT ? p.x_in0 + tg * 1024 : p.x_in1 + (tg - NTOK_PROMPT) * 1024) : p.out + tg * 1024;
; #pragma unroll
;         for (int m = 0; m < 8; ++m) xin16[nn][m] = *(const f32x4*)(xin + fbase + wr * 128 + m * 16 + fq * 4);
;       }
; #pragma unroll
;       for (int nn = 0; nn < 2; ++nn) {
;       const int n = n2 + nn;
;       const int tl = tbase + wc * 64 + n * 16 + fr;
;       const size_t tg = (size_t)c * CT + tl;
;       float ss = 0.f;
; #pragma unroll
;       for (int m = 0; m < 8; ++m) {
;         const int f = fbase + wr * 128 + m * 16 + fq * 4;
;         f32x4 xv = xin16[nn][m] + acc[m][n];
;         *(f32x4*)(p.out + tg * 1024 + f) = xv;
;         uint2 o; o.x = pk2(xv[0], xv[1]); o.y = pk2(xv[2], xv[3]);
;         *(uint2*)(WSU(x1b) + (size_t)tl * 1024 + f) = o;
;         ss += xv[0] * xv[0] + xv[1] * xv[1] + xv[2] * xv[2] + xv[3] * xv[3];
;       }
;       ss = xsum16(ss); ss = xsum32(ss);
;       if (fq == 0) atomicAdd(WSF(ssq1) + (size_t)l * CT + tl, ss);
.LBB0_178:
	v_lshlrev_b32_e32 v0, 2, v135
	v_or_b32_e32 v196, s4, v134
	s_add_i32 s4, s26, s18
	v_lshl_add_u64 v[126:127], s[18:19], 2, v[126:127]
	v_or_b32_e32 v194, s4, v0
	v_lshl_add_u64 v[126:127], s[26:27], 2, v[126:127]
	v_lshlrev_b32_e32 v0, 2, v0
	v_lshl_add_u64 v[126:127], v[126:127], 0, v[0:1]
	v_cmp_eq_u32_e64 s[4:5], 0, v135
	global_load_dwordx4 v[162:165], v[126:127], off
	global_load_dwordx4 v[154:157], v[126:127], off offset:64
	global_load_dwordx4 v[150:153], v[126:127], off offset:128
	global_load_dwordx4 v[146:149], v[126:127], off offset:192
	global_load_dwordx4 v[142:145], v[126:127], off offset:256
	global_load_dwordx4 v[138:141], v[126:127], off offset:320
	global_load_dwordx4 v[134:137], v[126:127], off offset:384
	s_nop 0
	global_load_dwordx4 v[126:129], v[126:127], off offset:448
	v_ashrrev_i32_e32 v197, 31, v196
	v_lshlrev_b64 v[200:201], 12, v[196:197]
	v_lshlrev_b64 v[202:203], 11, v[196:197]
	v_lshl_add_u64 v[200:201], s[10:11], 0, v[200:201]
	v_lshl_add_u64 v[202:203], s[20:21], 0, v[202:203]
	s_waitcnt vmcnt(0)
	v_mov_b32_e32 v240, 0x20000
	v_mov_b32_e32 v241, 0
	v_lshl_add_u64 v[244:245], v[208:209], 0, v[240:241]
	global_load_dwordx4 v[204:207], v[244:245], off
	global_load_dwordx4 v[216:219], v[244:245], off offset:64
	global_load_dwordx4 v[222:225], v[244:245], off offset:128
	global_load_dwordx4 v[226:229], v[244:245], off offset:192
	global_load_dwordx4 v[232:235], v[244:245], off offset:256
	global_load_dwordx4 v[236:239], v[244:245], off offset:320
	global_load_dwordx4 v[240:243], v[244:245], off offset:384
	s_nop 0
	global_load_dwordx4 v[244:247], v[244:245], off offset:448
	v_pk_add_f32 v[132:133], v[132:133], v[192:193]
	v_pk_add_f32 v[130:131], v[130:131], v[190:191]
	v_ashrrev_i32_e32 v195, 31, v194
	v_lshl_add_u64 v[190:191], v[194:195], 2, v[200:201]
	v_cvt_pk_bf16_f32 v192, v130, v131
	v_cvt_pk_bf16_f32 v193, v132, v133
	v_lshl_add_u64 v[200:201], v[194:195], 1, v[202:203]
	global_store_dwordx4 v[190:191], v[130:133], off
	global_store_dwordx2 v[200:201], v[192:193], off
	v_mul_f32_e32 v192, v131, v131
	v_pk_add_f32 v[124:125], v[124:125], v[188:189]
	v_pk_add_f32 v[122:123], v[122:123], v[186:187]
	v_fmac_f32_e32 v192, v130, v130
	global_store_dwordx4 v[190:191], v[122:125], off offset:64
	v_cvt_pk_bf16_f32 v130, v122, v123
	v_fmac_f32_e32 v192, v132, v132
	v_mul_f32_e32 v123, v123, v123
	v_fmac_f32_e32 v123, v122, v122
	v_fmac_f32_e32 v123, v124, v124
	v_fmac_f32_e32 v192, v133, v133
	v_cvt_pk_bf16_f32 v131, v124, v125
	v_fmac_f32_e32 v123, v125, v125
	v_pk_add_f32 v[120:121], v[120:121], v[184:185]
	v_pk_add_f32 v[118:119], v[118:119], v[182:183]
	global_store_dwordx2 v[200:201], v[130:131], off offset:32
	v_add_f32_e32 v124, v192, v123
	global_store_dwordx4 v[190:191], v[118:121], off offset:128
	v_cvt_pk_bf16_f32 v122, v118, v119
	v_cvt_pk_bf16_f32 v123, v120, v121
	v_mul_f32_e32 v119, v119, v119
	v_pk_add_f32 v[116:117], v[116:117], v[180:181]
	v_pk_add_f32 v[114:115], v[114:115], v[178:179]
	global_store_dwordx2 v[200:201], v[122:123], off offset:64
	v_fmac_f32_e32 v119, v118, v118
	global_store_dwordx4 v[190:191], v[114:117], off offset:192
	v_cvt_pk_bf16_f32 v118, v114, v115
	v_fmac_f32_e32 v119, v120, v120
	v_mul_f32_e32 v115, v115, v115
	v_fmac_f32_e32 v115, v114, v114
	v_fmac_f32_e32 v119, v121, v121
	v_fmac_f32_e32 v115, v116, v116
	v_add_f32_e32 v120, v124, v119
	v_cvt_pk_bf16_f32 v119, v116, v117
	v_fmac_f32_e32 v115, v117, v117
	v_pk_add_f32 v[112:113], v[112:113], v[176:177]
	v_pk_add_f32 v[110:111], v[110:111], v[174:175]
	global_store_dwordx2 v[200:201], v[118:119], off offset:96
	v_add_f32_e32 v116, v120, v115
	global_store_dwordx4 v[190:191], v[110:113], off offset:256
	v_cvt_pk_bf16_f32 v114, v110, v111
	v_cvt_pk_bf16_f32 v115, v112, v113
	v_mul_f32_e32 v111, v111, v111
	v_pk_add_f32 v[108:109], v[108:109], v[172:173]
	v_pk_add_f32 v[106:107], v[106:107], v[170:171]
	global_store_dwordx2 v[200:201], v[114:115], off offset:128
	v_fmac_f32_e32 v111, v110, v110
	global_store_dwordx4 v[190:191], v[106:109], off offset:320
	v_cvt_pk_bf16_f32 v110, v106, v107
	v_fmac_f32_e32 v111, v112, v112
	v_mul_f32_e32 v107, v107, v107
	v_fmac_f32_e32 v107, v106, v106
	v_fmac_f32_e32 v111, v113, v113
	v_fmac_f32_e32 v107, v108, v108
	v_add_f32_e32 v112, v116, v111
	v_cvt_pk_bf16_f32 v111, v108, v109
	v_fmac_f32_e32 v107, v109, v109
	v_pk_add_f32 v[104:105], v[104:105], v[168:169]
	v_pk_add_f32 v[102:103], v[102:103], v[166:167]
	global_store_dwordx2 v[200:201], v[110:111], off offset:160
	v_add_f32_e32 v108, v112, v107
	global_store_dwordx4 v[190:191], v[102:105], off offset:384
	v_cvt_pk_bf16_f32 v106, v102, v103
	v_cvt_pk_bf16_f32 v107, v104, v105
	v_mul_f32_e32 v103, v103, v103
	v_pk_add_f32 v[100:101], v[100:101], v[160:161]
	v_pk_add_f32 v[98:99], v[98:99], v[158:159]
	global_store_dwordx2 v[200:201], v[106:107], off offset:192
	v_fmac_f32_e32 v103, v102, v102
	global_store_dwordx4 v[190:191], v[98:101], off offset:448
	v_cvt_pk_bf16_f32 v102, v98, v99
	v_fmac_f32_e32 v103, v104, v104
	v_mul_f32_e32 v99, v99, v99
	v_fmac_f32_e32 v99, v98, v98
	v_fmac_f32_e32 v103, v105, v105
	v_fmac_f32_e32 v99, v100, v100
	v_add_f32_e32 v104, v108, v103
	v_fmac_f32_e32 v99, v101, v101
	v_add_f32_e32 v98, v104, v99
	v_mov_b32_e32 v99, v98
	s_nop 1
	v_permlane16_swap_b32_e32 v98, v99
	v_add_f32_e32 v98, v98, v99
	v_mov_b32_e32 v99, v98
	v_cvt_pk_bf16_f32 v103, v100, v101
	s_nop 0
	v_permlane32_swap_b32_e32 v98, v99
	v_lshl_add_u64 v[130:131], v[196:197], 2, s[22:23]
	global_store_dwordx2 v[200:201], v[102:103], off offset:224
	s_and_saveexec_b64 s[28:29], s[4:5]
	s_cbranch_execz .LBB0_180
	v_add_f32_e32 v98, v98, v99
	global_atomic_add_f32 v[130:131], v98, off
; DI float xsum16(float x) { const u32x2 r = __builtin_amdgcn_permlane16_swap(__float_as_uint(x), __float_as_uint(x), false, false); return __uint_as_float(r[0]) + __uint_as_float(r[1]); }
; DI float xsum32(float x) { const u32x2 r = __builtin_amdgcn_permlane32_swap(__float_as_uint(x), __float_as_uint(x), false, false); return __uint_as_float(r[0]) + __uint_as_float(r[1]); }
; template <int CT>
; DI void phase_g3(int c, int l) {
;     ...
; #pragma unroll
;       for (int nn = 0; nn < 2; ++nn) {
;       const int n = n2 + nn;
;       const int tl = tbase + wc * 64 + n * 16 + fr;
;       const size_t tg = (size_t)c * CT + tl;
;       float ss = 0.f;
; #pragma unroll
;       for (int m = 0; m < 8; ++m) {
;         const int f = fbase + wr * 128 + m * 16 + fq * 4;
;         f32x4 xv = xin16[nn][m] + acc[m][n];
;         *(f32x4*)(p.out + tg * 1024 + f) = xv;
;         uint2 o; o.x = pk2(xv[0], xv[1]); o.y = pk2(xv[2], xv[3]);
;         *(uint2*)(WSU(x1b) + (size_t)tl * 1024 + f) = o;
;         ss += xv[0] * xv[0] + xv[1] * xv[1] + xv[2] * xv[2] + xv[3] * xv[3];
;       }
;       ss = xsum16(ss); ss = xsum32(ss);
;       if (fq == 0) atomicAdd(WSF(ssq1) + (size_t)l * CT + tl, ss);
.LBB0_180:
	s_or_b64 exec, exec, s[28:29]
	v_mov_b32_e32 v166, 0x30000
	v_mov_b32_e32 v167, 0
	v_lshl_add_u64 v[158:159], v[208:209], 0, v[166:167]
	global_load_dwordx4 v[190:193], v[158:159], off
	global_load_dwordx4 v[186:189], v[158:159], off offset:64
	global_load_dwordx4 v[182:185], v[158:159], off offset:128
	global_load_dwordx4 v[178:181], v[158:159], off offset:192
	global_load_dwordx4 v[174:177], v[158:159], off offset:256
	global_load_dwordx4 v[170:173], v[158:159], off offset:320
	global_load_dwordx4 v[166:169], v[158:159], off offset:384
	s_nop 0
	global_load_dwordx4 v[158:161], v[158:159], off offset:448
	v_or_b32_e32 v98, 16, v196
	v_ashrrev_i32_e32 v99, 31, v98
	v_lshlrev_b64 v[100:101], 12, v[98:99]
	v_lshlrev_b64 v[98:99], 11, v[98:99]
	v_lshl_add_u64 v[100:101], s[10:11], 0, v[100:101]
	v_lshl_add_u64 v[98:99], s[20:21], 0, v[98:99]
	v_pk_add_f32 v[96:97], v[96:97], v[164:165]
	v_pk_add_f32 v[94:95], v[94:95], v[162:163]
	v_lshl_add_u64 v[100:101], v[194:195], 2, v[100:101]
	v_cvt_pk_bf16_f32 v102, v94, v95
	v_cvt_pk_bf16_f32 v103, v96, v97
	v_lshl_add_u64 v[98:99], v[194:195], 1, v[98:99]
	global_store_dwordx4 v[100:101], v[94:97], off
	global_store_dwordx2 v[98:99], v[102:103], off
	v_mul_f32_e32 v102, v95, v95
	v_pk_add_f32 v[92:93], v[92:93], v[156:157]
	v_pk_add_f32 v[90:91], v[90:91], v[154:155]
	v_fmac_f32_e32 v102, v94, v94
	global_store_dwordx4 v[100:101], v[90:93], off offset:64
	v_cvt_pk_bf16_f32 v94, v90, v91
	v_fmac_f32_e32 v102, v96, v96
	v_mul_f32_e32 v91, v91, v91
	v_fmac_f32_e32 v91, v90, v90
	v_fmac_f32_e32 v91, v92, v92
	v_fmac_f32_e32 v102, v97, v97
	v_cvt_pk_bf16_f32 v95, v92, v93
	v_fmac_f32_e32 v91, v93, v93
	v_pk_add_f32 v[88:89], v[88:89], v[152:153]
	v_pk_add_f32 v[86:87], v[86:87], v[150:151]
	global_store_dwordx2 v[98:99], v[94:95], off offset:32
	v_add_f32_e32 v92, v102, v91
	global_store_dwordx4 v[100:101], v[86:89], off offset:128
	v_cvt_pk_bf16_f32 v90, v86, v87
	v_cvt_pk_bf16_f32 v91, v88, v89
	v_mul_f32_e32 v87, v87, v87
	v_pk_add_f32 v[84:85], v[84:85], v[148:149]
	v_pk_add_f32 v[82:83], v[82:83], v[146:147]
	global_store_dwordx2 v[98:99], v[90:91], off offset:64
	v_fmac_f32_e32 v87, v86, v86
	global_store_dwordx4 v[100:101], v[82:85], off offset:192
	v_cvt_pk_bf16_f32 v86, v82, v83
	v_fmac_f32_e32 v87, v88, v88
	v_mul_f32_e32 v83, v83, v83
	v_fmac_f32_e32 v83, v82, v82
	v_fmac_f32_e32 v87, v89, v89
	v_fmac_f32_e32 v83, v84, v84
	v_add_f32_e32 v88, v92, v87
	v_cvt_pk_bf16_f32 v87, v84, v85
	v_fmac_f32_e32 v83, v85, v85
	v_pk_add_f32 v[80:81], v[80:81], v[144:145]
	v_pk_add_f32 v[78:79], v[78:79], v[142:143]
	global_store_dwordx2 v[98:99], v[86:87], off offset:96
	v_add_f32_e32 v84, v88, v83
	global_store_dwordx4 v[100:101], v[78:81], off offset:256
	v_cvt_pk_bf16_f32 v82, v78, v79
	v_cvt_pk_bf16_f32 v83, v80, v81
	v_mul_f32_e32 v79, v79, v79
	v_pk_add_f32 v[76:77], v[76:77], v[140:141]
	v_pk_add_f32 v[74:75], v[74:75], v[138:139]
	global_store_dwordx2 v[98:99], v[82:83], off offset:128
	v_fmac_f32_e32 v79, v78, v78
	global_store_dwordx4 v[100:101], v[74:77], off offset:320
	v_cvt_pk_bf16_f32 v78, v74, v75
	v_fmac_f32_e32 v79, v80, v80
	v_mul_f32_e32 v75, v75, v75
	v_fmac_f32_e32 v75, v74, v74
	v_fmac_f32_e32 v79, v81, v81
	v_fmac_f32_e32 v75, v76, v76
	v_add_f32_e32 v80, v84, v79
	v_cvt_pk_bf16_f32 v79, v76, v77
	v_fmac_f32_e32 v75, v77, v77
	v_pk_add_f32 v[72:73], v[72:73], v[136:137]
	v_pk_add_f32 v[70:71], v[70:71], v[134:135]
	global_store_dwordx2 v[98:99], v[78:79], off offset:160
	v_add_f32_e32 v76, v80, v75
	global_store_dwordx4 v[100:101], v[70:73], off offset:384
	v_cvt_pk_bf16_f32 v74, v70, v71
	v_cvt_pk_bf16_f32 v75, v72, v73
	v_mul_f32_e32 v71, v71, v71
	v_pk_add_f32 v[68:69], v[68:69], v[128:129]
	v_pk_add_f32 v[66:67], v[66:67], v[126:127]
	global_store_dwordx2 v[98:99], v[74:75], off offset:192
	v_fmac_f32_e32 v71, v70, v70
	global_store_dwordx4 v[100:101], v[66:69], off offset:448
	v_cvt_pk_bf16_f32 v70, v66, v67
	v_fmac_f32_e32 v71, v72, v72
	v_mul_f32_e32 v67, v67, v67
	v_fmac_f32_e32 v67, v66, v66
	v_fmac_f32_e32 v71, v73, v73
	v_fmac_f32_e32 v67, v68, v68
	v_add_f32_e32 v72, v76, v71
	v_fmac_f32_e32 v67, v69, v69
	v_add_f32_e32 v66, v72, v67
	v_mov_b32_e32 v67, v66
	s_nop 1
	v_permlane16_swap_b32_e32 v66, v67
	v_add_f32_e32 v66, v66, v67
	v_mov_b32_e32 v67, v66
	v_cvt_pk_bf16_f32 v71, v68, v69
	s_nop 0
	v_permlane32_swap_b32_e32 v66, v67
	global_store_dwordx2 v[98:99], v[70:71], off offset:224
	s_and_saveexec_b64 s[28:29], s[4:5]
	s_cbranch_execz .LBB0_182
	v_add_f32_e32 v66, v66, v67
	global_atomic_add_f32 v[130:131], v66, off offset:64

; template <int CT>
; DI void phase_g3(int c, int l) {
;     ...
;       for (int nn = 0; nn < 2; ++nn) {
;         const size_t tg = (size_t)c * CT + tbase + wc * 64 + (n2 + nn) * 16 + fr;
;         const float* xin = l == 0 ? (tg < NTOK_PROMPT ? p.x_in0 + tg * 1024 : p.x_in1 + (tg - NTOK_PROMPT) * 1024) : p.out + tg * 1024;
; #pragma unroll
;         for (int m = 0; m < 8; ++m) xin16[nn][m] = *(const f32x4*)(xin + fbase + wr * 128 + m * 16 + fq * 4);
.LBB0_189:
	v_lshl_add_u64 v[66:67], s[18:19], 2, v[68:69]
	v_lshl_add_u64 v[66:67], s[26:27], 2, v[66:67]
	v_lshl_add_u64 v[66:67], v[66:67], 0, v[0:1]
	v_or_b32_e32 v198, 48, v198
	s_mov_b64 s[28:29], -1
	s_and_b64 vcc, exec, s[8:9]
	v_lshlrev_b64 v[66:67], 12, v[198:199]
	s_cbranch_vccnz .LBB0_191
	v_lshl_add_u64 v[68:69], s[16:17], 0, v[66:67]
	s_mov_b64 s[28:29], 0

; DI float xsum16(float x) { const u32x2 r = __builtin_amdgcn_permlane16_swap(__float_as_uint(x), __float_as_uint(x), false, false); return __uint_as_float(r[0]) + __uint_as_float(r[1]); }
; DI float xsum32(float x) { const u32x2 r = __builtin_amdgcn_permlane32_swap(__float_as_uint(x), __float_as_uint(x), false, false); return __uint_as_float(r[0]) + __uint_as_float(r[1]); }
; template <int CT>
; DI void phase_g3(int c, int l) {
;     ...
;       for (int nn = 0; nn < 2; ++nn) {
;         const size_t tg = (size_t)c * CT + tbase + wc * 64 + (n2 + nn) * 16 + fr;
;         const float* xin = l == 0 ? (tg < NTOK_PROMPT ? p.x_in0 + tg * 1024 : p.x_in1 + (tg - NTOK_PROMPT) * 1024) : p.out + tg * 1024;
; #pragma unroll
;         for (int m = 0; m < 8; ++m) xin16[nn][m] = *(const f32x4*)(xin + fbase + wr * 128 + m * 16 + fq * 4);
;       }
; #pragma unroll
;       for (int nn = 0; nn < 2; ++nn) {
;       const int n = n2 + nn;
;       const int tl = tbase + wc * 64 + n * 16 + fr;
;       const size_t tg = (size_t)c * CT + tl;
;       float ss = 0.f;
; #pragma unroll
;       for (int m = 0; m < 8; ++m) {
;         const int f = fbase + wr * 128 + m * 16 + fq * 4;
;         f32x4 xv = xin16[nn][m] + acc[m][n];
;         *(f32x4*)(p.out + tg * 1024 + f) = xv;
;         uint2 o; o.x = pk2(xv[0], xv[1]); o.y = pk2(xv[2], xv[3]);
;         *(uint2*)(WSU(x1b) + (size_t)tl * 1024 + f) = o;
;         ss += xv[0] * xv[0] + xv[1] * xv[1] + xv[2] * xv[2] + xv[3] * xv[3];
;       }
;       ss = xsum16(ss); ss = xsum32(ss);
;       if (fq == 0) atomicAdd(WSF(ssq1) + (size_t)l * CT + tl, ss);
.LBB0_196:
	v_lshl_add_u64 v[66:67], s[18:19], 2, v[68:69]
	v_lshl_add_u64 v[66:67], s[26:27], 2, v[66:67]
	v_lshl_add_u64 v[66:67], v[66:67], 0, v[0:1]
	s_nop 0
	v_or_b32_e32 v132, 32, v196
	v_ashrrev_i32_e32 v133, 31, v132
	v_lshlrev_b64 v[134:135], 12, v[132:133]
	v_lshlrev_b64 v[132:133], 11, v[132:133]
	v_lshl_add_u64 v[134:135], s[10:11], 0, v[134:135]
	v_lshl_add_u64 v[132:133], s[20:21], 0, v[132:133]
	s_waitcnt vmcnt(16)
	v_mov_b32_e32 v126, v204
	v_mov_b32_e32 v127, v205
	v_mov_b32_e32 v128, v206
	v_mov_b32_e32 v129, v207
	v_mov_b32_e32 v122, v216
	v_mov_b32_e32 v123, v217
	v_mov_b32_e32 v124, v218
	v_mov_b32_e32 v125, v219
	v_mov_b32_e32 v118, v222
	v_mov_b32_e32 v119, v223
	v_mov_b32_e32 v120, v224
	v_mov_b32_e32 v121, v225
	v_mov_b32_e32 v114, v226
	v_mov_b32_e32 v115, v227
	v_mov_b32_e32 v116, v228
	v_mov_b32_e32 v117, v229
	v_mov_b32_e32 v110, v232
	v_mov_b32_e32 v111, v233
	v_mov_b32_e32 v112, v234
	v_mov_b32_e32 v113, v235
	v_mov_b32_e32 v106, v236
	v_mov_b32_e32 v107, v237
	v_mov_b32_e32 v108, v238
	v_mov_b32_e32 v109, v239
	v_mov_b32_e32 v102, v240
	v_mov_b32_e32 v103, v241
	v_mov_b32_e32 v104, v242
	v_mov_b32_e32 v105, v243
	v_mov_b32_e32 v94, v244
	v_mov_b32_e32 v95, v245
	v_mov_b32_e32 v96, v246
	v_mov_b32_e32 v97, v247
	v_mov_b32_e32 v98, v190
	v_mov_b32_e32 v99, v191
	v_mov_b32_e32 v100, v192
	v_mov_b32_e32 v101, v193
	v_mov_b32_e32 v90, v186
	v_mov_b32_e32 v91, v187
	v_mov_b32_e32 v92, v188
	v_mov_b32_e32 v93, v189
	v_mov_b32_e32 v86, v182
	v_mov_b32_e32 v87, v183
	v_mov_b32_e32 v88, v184
	v_mov_b32_e32 v89, v185
	v_mov_b32_e32 v82, v178
	v_mov_b32_e32 v83, v179
	v_mov_b32_e32 v84, v180
	v_mov_b32_e32 v85, v181
	v_mov_b32_e32 v78, v174
	v_mov_b32_e32 v79, v175
	v_mov_b32_e32 v80, v176
	v_mov_b32_e32 v81, v177
	v_mov_b32_e32 v74, v170
	v_mov_b32_e32 v75, v171
	v_mov_b32_e32 v76, v172
	v_mov_b32_e32 v77, v173
	v_mov_b32_e32 v70, v166
	v_mov_b32_e32 v71, v167
	v_mov_b32_e32 v72, v168
	v_mov_b32_e32 v73, v169
	v_mov_b32_e32 v66, v158
	v_mov_b32_e32 v67, v159
	v_mov_b32_e32 v68, v160
	v_mov_b32_e32 v69, v161
	v_pk_add_f32 v[64:65], v[64:65], v[128:129]
	v_pk_add_f32 v[62:63], v[62:63], v[126:127]
	v_lshl_add_u64 v[126:127], v[194:195], 2, v[134:135]
	v_cvt_pk_bf16_f32 v128, v62, v63
	v_cvt_pk_bf16_f32 v129, v64, v65
	v_lshl_add_u64 v[132:133], v[194:195], 1, v[132:133]
	v_mul_f32_e32 v0, v63, v63
	v_pk_add_f32 v[60:61], v[60:61], v[124:125]
	v_pk_add_f32 v[58:59], v[58:59], v[122:123]
	global_store_dwordx4 v[126:127], v[62:65], off
	global_store_dwordx2 v[132:133], v[128:129], off
	v_fmac_f32_e32 v0, v62, v62
	global_store_dwordx4 v[126:127], v[58:61], off offset:64
	v_cvt_pk_bf16_f32 v62, v58, v59
	v_fmac_f32_e32 v0, v64, v64
	v_mul_f32_e32 v59, v59, v59
	v_fmac_f32_e32 v59, v58, v58
	v_fmac_f32_e32 v59, v60, v60
	v_fmac_f32_e32 v0, v65, v65
	v_cvt_pk_bf16_f32 v63, v60, v61
	v_fmac_f32_e32 v59, v61, v61
	v_pk_add_f32 v[56:57], v[56:57], v[120:121]
	v_pk_add_f32 v[54:55], v[54:55], v[118:119]
	global_store_dwordx2 v[132:133], v[62:63], off offset:32
	v_add_f32_e32 v0, v0, v59
	global_store_dwordx4 v[126:127], v[54:57], off offset:128
	v_cvt_pk_bf16_f32 v58, v54, v55
	v_cvt_pk_bf16_f32 v59, v56, v57
	v_mul_f32_e32 v55, v55, v55
	v_pk_add_f32 v[52:53], v[52:53], v[116:117]
	v_pk_add_f32 v[50:51], v[50:51], v[114:115]
	global_store_dwordx2 v[132:133], v[58:59], off offset:64
	v_fmac_f32_e32 v55, v54, v54
	global_store_dwordx4 v[126:127], v[50:53], off offset:192
	v_cvt_pk_bf16_f32 v54, v50, v51
	v_fmac_f32_e32 v55, v56, v56
	v_mul_f32_e32 v51, v51, v51
	v_fmac_f32_e32 v51, v50, v50
	v_fmac_f32_e32 v55, v57, v57
	v_fmac_f32_e32 v51, v52, v52
	v_add_f32_e32 v0, v0, v55
	v_cvt_pk_bf16_f32 v55, v52, v53
	v_fmac_f32_e32 v51, v53, v53
	v_pk_add_f32 v[48:49], v[48:49], v[112:113]
	v_pk_add_f32 v[46:47], v[46:47], v[110:111]
	global_store_dwordx2 v[132:133], v[54:55], off offset:96
	v_add_f32_e32 v0, v0, v51
	global_store_dwordx4 v[126:127], v[46:49], off offset:256
	v_cvt_pk_bf16_f32 v50, v46, v47
	v_cvt_pk_bf16_f32 v51, v48, v49
	v_mul_f32_e32 v47, v47, v47
	v_pk_add_f32 v[44:45], v[44:45], v[108:109]
	v_pk_add_f32 v[42:43], v[42:43], v[106:107]
	global_store_dwordx2 v[132:133], v[50:51], off offset:128
	v_fmac_f32_e32 v47, v46, v46
	global_store_dwordx4 v[126:127], v[42:45], off offset:320
	v_cvt_pk_bf16_f32 v46, v42, v43
	v_fmac_f32_e32 v47, v48, v48
	v_mul_f32_e32 v43, v43, v43
	v_fmac_f32_e32 v43, v42, v42
	v_fmac_f32_e32 v47, v49, v49
	v_fmac_f32_e32 v43, v44, v44
	v_add_f32_e32 v0, v0, v47
	v_cvt_pk_bf16_f32 v47, v44, v45
	v_fmac_f32_e32 v43, v45, v45
	v_pk_add_f32 v[40:41], v[40:41], v[104:105]
	v_pk_add_f32 v[38:39], v[38:39], v[102:103]
	global_store_dwordx2 v[132:133], v[46:47], off offset:160
	v_add_f32_e32 v0, v0, v43
	global_store_dwordx4 v[126:127], v[38:41], off offset:384
	v_cvt_pk_bf16_f32 v42, v38, v39
	v_cvt_pk_bf16_f32 v43, v40, v41
	v_mul_f32_e32 v39, v39, v39
	v_pk_add_f32 v[36:37], v[36:37], v[96:97]
	v_pk_add_f32 v[34:35], v[34:35], v[94:95]
	global_store_dwordx2 v[132:133], v[42:43], off offset:192
	v_fmac_f32_e32 v39, v38, v38
	global_store_dwordx4 v[126:127], v[34:37], off offset:448
	v_cvt_pk_bf16_f32 v38, v34, v35
	v_fmac_f32_e32 v39, v40, v40
	v_mul_f32_e32 v35, v35, v35
	v_fmac_f32_e32 v35, v34, v34
	v_fmac_f32_e32 v39, v41, v41
	v_fmac_f32_e32 v35, v36, v36
	v_add_f32_e32 v0, v0, v39
	v_fmac_f32_e32 v35, v37, v37
	v_add_f32_e32 v0, v0, v35
	v_mov_b32_e32 v34, v0
	s_nop 1
	v_permlane16_swap_b32_e32 v0, v34
	v_add_f32_e32 v0, v0, v34
	v_mov_b32_e32 v34, v0
	v_cvt_pk_bf16_f32 v39, v36, v37
	s_nop 0
	v_permlane32_swap_b32_e32 v0, v34
	global_store_dwordx2 v[132:133], v[38:39], off offset:224
	s_and_saveexec_b64 s[6:7], s[4:5]
	s_cbranch_execz .LBB0_198
	v_add_f32_e32 v0, v0, v34
	global_atomic_add_f32 v[130:131], v0, off offset:128

; #define LOAD_PARAMS() KParams kq_ = (KParams)__builtin_amdgcn_kernarg_segment_ptr(); asm volatile("" : "+s"(kq_)); const Params p = *kq_
; template <int CT>
; __global__ void __launch_bounds__(NTHREADS) mega_kernel(Params p) {
;     ...
; #pragma unroll 1
;   for (int ph = 0; ph < nph; ++ph) {
;     run_phase<CT>(ph);
;     if (ph + 1 < nph) {
;       LOAD_PARAMS();
;       xcd_barrier((unsigned*)(p.ws + WS<CT>::bar), x, nloc, nx, k);
;       ++k;
;     }
;   }
; }
.LBB0_726:
	s_endpgm
	s_nop 0
	s_nop 0
	s_nop 0
	s_nop 0
	s_nop 0
	s_nop 0
	s_nop 0
	s_nop 0
	s_nop 0
	s_nop 0
	s_nop 0
	s_nop 0
	s_nop 0
	s_nop 0
	s_nop 0
	s_endpgm
